# v034 + sgu/pool loop headers no longer drain the previous unit's output stores
# speedup vs baseline: 1.0130x; 1.0038x over previous
; #define LAS __attribute__((address_space(3)))
; __device__ __forceinline__ void pool_phase(LAS unsigned char* lds, const bf16_t* PROJ, const bf16_t* PW, const float* pscale, bf16_t* Y, float* SS, int bx, int G) {
;     ...
;     const int g = bx & 3, step = G >> 2; int pt = bx >> 2;
;     if (step == 0 || bx >= 4 * step || pt >= 256) return;
;     bf16x8 wf[2][8];
; #pragma unroll
;     for (int j = 0; j < 2; ++j)
; #pragma unroll
;         for (int ks = 0; ks < 8; ++ks) wf[j][ks] = *(const bf16x8*)(PW + (size_t)(g * 256 + 32 * wid + 8 * (fr >> 2) + 4 * j + (fr & 3)) * 256 + 32 * ks + 8 * fq);
;     u32x4 stg[5]; u32x4 gt[4];
;     ...
;     POOL_LOAD(pt);
;     const int cp = tid & 127, tb = tid >> 7, w = 2 << g, t_start = 16 * tb;
;     const LAS unsigned* xs = (const LAS unsigned*)(lds + PL_XS) + cp;
;     LAS float* ssw = (LAS float*)(lds + PL_SSW);
;     for (; pt < 256; pt += step) {
;         const int T0 = pt * 64, pos0 = T0 % SEQ;
; #pragma unroll
;         for (int it = 0; it < 5; ++it) { const int p = tid + 512 * it, sb_ = p >> 6, row = 16 * (sb_ >> 3) + ((p >> 2) & 15), c16 = 4 * (sb_ & 7) + (p & 3); *(LAS u32x4*)(lds + PL_XS + row * 512 + c16 * 16) = stg[it]; }
; #pragma unroll
;         for (int m = 0; m < 4; ++m) gt[m] = *(const u32x4*)PJ(PROJ, T0 + 16 * m + fr, COL_GA + g * 256 + 32 * wid + 8 * fq);
.LBB0_470:
	s_or_b64 exec, exec, s[10:11]
	s_ashr_i32 s77, s3, 2
	s_lshl_b32 s78, 2, s74
	s_lshl_b32 s10, s74, 2
	s_add_u32 s58, s46, s10
	s_addc_u32 s59, s47, 0
	s_cmp_eq_u32 s74, 0
	s_cselect_b64 s[10:11], -1, 0
	s_cmp_gt_u32 s74, 1
	s_cselect_b64 s[12:13], -1, 0
	s_cmp_eq_u32 s74, 3
	s_cselect_b64 s[14:15], -1, 0
	s_add_i32 s19, s16, 0x400
	s_ashr_i32 s60, s19, 8
	s_ashr_i32 s61, s60, 31
	v_mov_b32_e32 v104, s62
	s_add_i32 s62, 0, 0x12400
	s_lshl_b64 s[60:61], s[60:61], 23
	v_and_b32_e32 v86, 48, v86
	v_and_b32_e32 v108, 0x1c0, v88
	s_add_u32 s60, s36, s60
	v_add3_u32 v108, 0, v108, v86
	v_lshlrev_b32_e32 v86, 3, v103
	s_addc_u32 s61, s37, s61
	s_lshl_b32 s17, s17, 9
	v_lshlrev_b32_e32 v103, 5, v88
	s_and_b32 s17, s17, 0xe00
	v_and_b32_e32 v103, 0x1e0, v103
	v_and_b32_e32 v86, 24, v86
	v_or3_b32 v86, v86, v103, s17
	v_lshlrev_b32_e32 v86, 1, v86
	v_lshl_add_u64 v[132:133], s[60:61], 0, v[86:87]
	v_or_b32_e32 v86, s16, v102
	v_mov_b32_e32 v105, s63
	v_ashrrev_i32_e32 v107, 3, v88
	v_ashrrev_i32_e32 v87, 31, v86
	v_and_b32_e32 v1, -16, v107
	v_lshl_add_u64 v[134:135], v[86:87], 2, v[104:105]
	s_movk_i32 s60, 0x210
	v_or_b32_e32 v174, 15, v107
	v_mov_b32_e32 v105, 0x6300
	s_and_b32 s18, s18, 0x3fffffc0
	v_lshlrev_b32_e32 v87, 9, v93
	v_lshlrev_b32_e32 v93, 9, v101
	v_mul_lo_u32 v101, v1, s60
	v_mul_lo_u32 v102, v174, s60
	v_mad_u32_u24 v105, v97, s60, v105
	s_add_i32 s60, s86, s77
	v_lshlrev_b32_e32 v86, 1, v86
	s_lshl_b32 s18, s18, 2
	s_lshl_b32 s60, s60, 6
	v_and_b32_e32 v106, 0x7f, v88
	s_ashr_i32 s80, s16, 6
	s_bfe_u32 s16, s16, 0x10005
	v_and_b32_e32 v157, 48, v86
	s_add_i32 s18, s18, s62
	v_lshlrev_b32_e32 v86, 9, v91
	v_lshlrev_b32_e32 v91, 9, v98
	v_mov_b32_e32 v98, 0x1e00
	v_add_u32_e32 v92, s60, v92
	v_lshl_add_u32 v106, v106, 2, 0
	v_lshl_add_u32 v103, v90, 4, 0
	v_mov_b32_e32 v156, s16
	v_cmp_eq_u32_e64 s[16:17], 0, v90
	v_lshl_add_u32 v158, v97, 2, s18
	v_cmp_gt_i32_e64 s[18:19], 64, v88
	v_lshl_add_u32 v159, v88, 2, s62
	v_lshlrev_b32_e32 v90, 9, v95
	v_lshlrev_b32_e32 v95, 9, v1
	v_lshl_or_b32 v98, v107, 9, v98
	v_mul_u32_u24_e32 v104, 0x210, v97
	v_add_u32_e32 v100, s60, v100
	v_add_u32_e32 v96, s60, v96
	v_add_u32_e32 v94, s60, v94
	v_add3_u32 v178, v92, v89, -16
	v_add_u32_e32 v92, s60, v99
	s_lshl_b32 s60, s86, 2
	v_add_u32_e32 v180, s76, v88
	v_lshlrev_b32_e32 v88, 6, v97
	v_add_u32_e32 v183, v108, v86
	v_mbcnt_lo_u32_b32 v86, -1, 0
	s_mov_b32 s79, 0
	s_ashr_i32 s81, s80, 31
	v_or_b32_e32 v160, 1, v1
	v_or_b32_e32 v161, 2, v1
	v_or_b32_e32 v162, 3, v1
	v_or_b32_e32 v163, 4, v1
	v_or_b32_e32 v164, 5, v1
	v_or_b32_e32 v165, 6, v1
	v_or_b32_e32 v166, 7, v1
	v_or_b32_e32 v167, 8, v1
	v_or_b32_e32 v168, 9, v1
	v_or_b32_e32 v169, 10, v1
	v_or_b32_e32 v170, 11, v1
	v_or_b32_e32 v171, 12, v1
	v_or_b32_e32 v172, 13, v1
	v_or_b32_e32 v173, 14, v1
	v_add3_u32 v175, v100, v89, -16
	s_lshl_b32 s82, s77, 6
	v_add3_u32 v176, v96, v89, -16
	v_add3_u32 v177, v94, v89, -16
	v_add3_u32 v179, v92, v89, -16
	s_or_b32 s60, s60, 3
	v_lshl_or_b32 v182, s86, 12, v88
	s_lshl_b32 s83, s77, 12
	v_add_u32_e32 v184, v108, v87
	v_add_u32_e32 v185, v108, v90
	v_add_u32_e32 v186, v108, v91
	v_add_u32_e32 v187, v108, v93
	v_add_u32_e32 v188, v106, v95
	v_add_u32_e32 v189, v106, v98
	v_add_u32_e32 v190, v106, v102
	v_add_u32_e32 v191, v103, v104
	v_add_u32_e32 v192, v103, v105
	s_movk_i32 s87, 0x3c0
	v_mbcnt_hi_u32_b32 v193, -1, v86
	v_add_u32_e32 v194, v106, v101
	s_add_i32 s62, s60, -3
	s_ashr_i32 s63, s62, 31
	s_lshl_b64 s[62:63], s[62:63], 13
	v_lshl_add_u64 v[86:87], v[132:133], 0, s[62:63]
	s_add_i32 s62, s60, -2
	s_ashr_i32 s63, s62, 31
	s_lshl_b64 s[62:63], s[62:63], 13
	v_lshl_add_u64 v[88:89], v[132:133], 0, s[62:63]
	s_add_i32 s62, s60, -1
	s_ashr_i32 s63, s62, 31
	s_lshl_b64 s[62:63], s[62:63], 13
	s_ashr_i32 s61, s60, 31
	global_load_dwordx4 v[98:101], v[86:87], off
	global_load_dwordx4 v[94:97], v[88:89], off
	v_lshl_add_u64 v[86:87], v[132:133], 0, s[62:63]
	s_lshl_b64 s[62:63], s[60:61], 13
	v_lshl_add_u64 v[88:89], v[132:133], 0, s[62:63]
	global_load_dwordx4 v[90:93], v[86:87], off
	s_nop 0
	global_load_dwordx4 v[86:89], v[88:89], off
	s_add_i32 s61, s86, s77
	s_cmpk_gt_i32 s61, 0xff
	s_cselect_b64 s[62:63], -1, 0
	s_and_b64 vcc, exec, s[62:63]
	s_waitcnt vmcnt(4)
	s_branch .Lpool_body

; #define LAS __attribute__((address_space(3)))
; __device__ __forceinline__ void pool_phase(LAS unsigned char* lds, const bf16_t* PROJ, const bf16_t* PW, const float* pscale, bf16_t* Y, float* SS, int bx, int G) {
;     ...
;     for (; pt < 256; pt += step) {
;         const int T0 = pt * 64, pos0 = T0 % SEQ;
; #pragma unroll
;         for (int it = 0; it < 5; ++it) { const int p = tid + 512 * it, sb_ = p >> 6, row = 16 * (sb_ >> 3) + ((p >> 2) & 15), c16 = 4 * (sb_ & 7) + (p & 3); *(LAS u32x4*)(lds + PL_XS + row * 512 + c16 * 16) = stg[it]; }
; #pragma unroll
;         for (int m = 0; m < 4; ++m) gt[m] = *(const u32x4*)PJ(PROJ, T0 + 16 * m + fr, COL_GA + g * 256 + 32 * wid + 8 * fq);
;         __syncthreads();
;         if (pt + step < 256) POOL_LOAD(pt + step);
.LBB0_472:
	s_add_i32 s62, s60, -3
	s_ashr_i32 s63, s62, 31
	s_lshl_b64 s[62:63], s[62:63], 13
	v_lshl_add_u64 v[86:87], v[132:133], 0, s[62:63]
	s_add_i32 s62, s60, -2
	s_ashr_i32 s63, s62, 31
	s_lshl_b64 s[62:63], s[62:63], 13
	v_lshl_add_u64 v[88:89], v[132:133], 0, s[62:63]
	s_add_i32 s62, s60, -1
	s_ashr_i32 s63, s62, 31
	s_lshl_b64 s[62:63], s[62:63], 13
	s_ashr_i32 s61, s60, 31
	global_load_dwordx4 v[98:101], v[86:87], off
	global_load_dwordx4 v[94:97], v[88:89], off
	v_lshl_add_u64 v[86:87], v[132:133], 0, s[62:63]
	s_lshl_b64 s[62:63], s[60:61], 13
	v_lshl_add_u64 v[88:89], v[132:133], 0, s[62:63]
	global_load_dwordx4 v[90:93], v[86:87], off
	s_nop 0
	global_load_dwordx4 v[86:89], v[88:89], off
	s_add_i32 s61, s86, s77
	s_cmpk_gt_i32 s61, 0xff
	s_cselect_b64 s[62:63], -1, 0
	s_and_b64 vcc, exec, s[62:63]
	s_waitcnt vmcnt(8)
.Lpool_body:
	ds_write_b128 v183, v[70:73]
	ds_write_b128 v184, v[66:69]
	ds_write_b128 v185, v[74:77]
	ds_write_b128 v186, v[78:81]
	ds_write_b128 v187, v[82:85]
	s_waitcnt lgkmcnt(0)
	s_barrier
	s_cbranch_vccnz .LBB0_484
	s_and_b32 s70, s61, 63
	s_cmp_eq_u32 s70, 0
	s_cselect_b64 s[70:71], -1, 0
	s_and_b64 s[72:73], s[70:71], s[0:1]
	s_xor_b64 s[88:89], s[72:73], -1
	v_mov_b32_e32 v74, 0
	v_mov_b32_e32 v70, 0
	v_mov_b32_e32 v71, 0
	v_mov_b32_e32 v72, 0
	v_mov_b32_e32 v73, 0
	s_and_saveexec_b64 s[72:73], s[88:89]
	s_cbranch_execz .LBB0_475
	v_add_u32_e32 v66, s79, v179
	v_ashrrev_i32_e32 v66, 4, v66
	v_ashrrev_i32_e32 v67, 31, v66
	v_lshlrev_b64 v[66:67], 13, v[66:67]
	v_lshl_add_u64 v[66:67], v[130:131], 0, v[66:67]
	global_load_dwordx4 v[70:73], v[66:67], off

; #define LAS __attribute__((address_space(3)))
; __device__ __forceinline__ void sgu_phase(LAS unsigned char* lds, const bf16_t* PROJ, const float* VST, const bf16_t* SW, const float* ln_g, const float* ln_b, const float* sgu_b,
;                                           bf16_t* Y, float* SS, int bx, int G) {
;     ...
;     const int tid = tid_, lane = tid & 63, wid = __builtin_amdgcn_readfirstlane(tid >> 6), fr = lane & 15, fq = lane >> 4;
;     const int h = bx & 7, step = G >> 3; int cc = bx >> 3;
;     if (step == 0 || bx >= 8 * step || cc >= 128) return;
;     LAS float* meanp = (LAS float*)(lds + SG_MEAN); LAS float* rstdp = (LAS float*)(lds + SG_RSTD); LAS float* ssw = (LAS float*)(lds + SG_SSW);
; #pragma unroll
;     for (int it = 0; it < 4; ++it) { const int p = tid + 512 * it, row = p >> 4, c16 = p & 15;
;         *(LAS u32x4*)(lds + SG_W + row * SG_ROWB + c16 * 16) = *(const u32x4*)(SW + (size_t)(h * 128 + row) * 128 + c16 * 8); }
;     const int dch = tid & 127; const float gch = ln_g[h * 128 + dch], bch = ln_b[h * 128 + dch];
;     const int dp = wid >> 1, th = wid & 1;
;     float bias[4];
; #pragma unroll
;     for (int jj = 0; jj < 4; ++jj) bias[jj] = sgu_b[h * 128 + 16 * (4 * th + jj) + fr];
;     u32x4 vst[4]; f32x4 sp[2];
;     ...
;     SGU_LOAD(cc);
.LBB0_630:
	s_ashr_i32 s20, s2, 3
	s_cmp_lt_u32 s3, 8
	s_cselect_b64 s[0:1], -1, 0
	s_and_b32 s4, s3, -8
	s_cmp_ge_i32 s2, s4
	s_cselect_b64 s[4:5], -1, 0
	s_cmpk_gt_i32 s20, 0x7f
	s_cselect_b64 s[6:7], -1, 0
	s_or_b64 s[4:5], s[6:7], s[4:5]
	v_mov_b32_e32 v26, v0
	s_or_b64 s[0:1], s[0:1], s[4:5]
	v_ashrrev_i32_e32 v27, 6, v26
	s_and_b64 vcc, exec, s[0:1]
	v_readfirstlane_b32 s7, v27
	s_cbranch_vccnz .LBB0_664
	s_and_b32 s6, s2, 7
	s_lshl_b32 s4, s6, 7
	v_ashrrev_i32_e32 v31, 4, v26
	v_and_b32_e32 v30, 15, v26
	v_add_u32_e32 v2, s4, v31
	v_lshlrev_b32_e32 v98, 4, v30
	v_mov_b32_e32 v99, 0
	v_ashrrev_i32_e32 v3, 31, v2
	v_add_u32_e32 v1, 0x200, v26
	v_lshl_add_u64 v[10:11], s[68:69], 0, v[98:99]
	v_lshlrev_b64 v[2:3], 8, v[2:3]
	v_ashrrev_i32_e32 v32, 4, v1
	v_lshl_add_u64 v[12:13], v[10:11], 0, v[2:3]
	v_add_u32_e32 v2, s4, v32
	v_ashrrev_i32_e32 v3, 31, v2
	v_add_u32_e32 v1, 0x400, v26
	v_lshlrev_b64 v[2:3], 8, v[2:3]
	v_ashrrev_i32_e32 v33, 4, v1
	v_lshl_add_u64 v[14:15], v[10:11], 0, v[2:3]
	s_waitcnt lgkmcnt(0)
	global_load_dwordx4 v[2:5], v[12:13], off
	global_load_dwordx4 v[6:9], v[14:15], off
	v_add_u32_e32 v12, s4, v33
	v_ashrrev_i32_e32 v13, 31, v12
	v_add_u32_e32 v1, 0x600, v26
	v_lshlrev_b64 v[12:13], 8, v[12:13]
	s_waitcnt vmcnt(0)
	v_ashrrev_i32_e32 v34, 4, v1
	v_lshl_add_u64 v[18:19], v[10:11], 0, v[12:13]
	v_add_u32_e32 v12, s4, v34
	v_ashrrev_i32_e32 v13, 31, v12
	v_lshlrev_b64 v[12:13], 8, v[12:13]
	v_lshl_add_u64 v[20:21], v[10:11], 0, v[12:13]
	global_load_dwordx4 v[10:13], v[18:19], off
	global_load_dwordx4 v[14:17], v[20:21], off
	s_lshl_b32 s5, s2, 22
	s_ashr_i32 s21, s3, 3
	v_lshrrev_b32_e32 v1, 4, v26
	v_and_b32_e32 v37, 3, v26
	s_and_b32 s5, s5, 0x1800000
	v_and_b32_e32 v36, 0x7f, v26
	v_lshlrev_b32_e32 v18, 3, v26
	v_and_or_b32 v1, v1, 12, v37
	s_add_u32 s8, s36, s5
	v_and_b32_e32 v28, 0x1e0, v18
	v_or_b32_e32 v18, s4, v36
	v_lshlrev_b32_e32 v1, 3, v1
	s_addc_u32 s9, s37, 0
	s_add_i32 s13, 0, 0x11000
	s_movk_i32 s12, 0x110
	v_lshlrev_b32_e32 v19, 2, v18
	s_and_b32 s17, s7, 1
	v_or_b32_e32 v20, s4, v1
	v_add_u32_e32 v18, s13, v98
	v_or_b32_e32 v29, s4, v30
	v_and_b32_e32 v39, 24, v1
	global_load_dword v1, v19, s[64:65]
	global_load_dword v108, v19, s[66:67]
	s_lshl_b32 s18, s17, 6
	v_lshlrev_b32_e32 v40, 4, v20
	v_mad_u64_u32 v[20:21], s[10:11], v31, s12, v[18:19]
	v_mad_u64_u32 v[22:23], s[10:11], v32, s12, v[18:19]
	v_mad_u64_u32 v[24:25], s[10:11], v33, s12, v[18:19]
	v_mad_u64_u32 v[18:19], s[10:11], v34, s12, v[18:19]
	v_or_b32_e32 v19, s18, v29
	s_lshl_b32 s16, s20, 7
	v_and_b32_e32 v21, 0xe00, v40
	v_lshlrev_b32_e32 v19, 2, v19
	v_or3_b32 v21, v39, v28, v21
	global_load_dword v109, v19, s[38:39]
	global_load_dword v110, v19, s[38:39] offset:64
	global_load_dword v111, v19, s[38:39] offset:128
	global_load_dword v112, v19, s[38:39] offset:192
	v_lshlrev_b32_e32 v98, 1, v21
	s_mov_b64 s[0:1], 0x6000000
	v_lshl_add_u64 v[28:29], s[8:9], 0, v[98:99]
	v_lshl_add_u64 v[100:101], v[28:29], 0, s[0:1]
	v_ashrrev_i32_e32 v42, 2, v26
	v_lshlrev_b32_e32 v98, 5, v37
	v_lshlrev_b32_e32 v43, 4, v26
	v_and_b32_e32 v43, 48, v43
	v_and_b32_e32 v44, 0xc0, v26
	v_add3_u32 v43, 0, v44, v43
	v_mbcnt_lo_u32_b32 v44, -1, 0
	v_mbcnt_hi_u32_b32 v44, -1, v44
	s_ashr_i32 s8, s7, 1
	v_and_b32_e32 v46, 64, v44
	v_xor_b32_e32 v45, 1, v44
	v_add_u32_e32 v46, 64, v46
	s_lshl_b32 s9, s8, 5
	v_cmp_lt_i32_e32 vcc, v45, v46
	s_add_i32 s10, s9, s4
	s_add_i32 s4, s10, 0x800
	v_cndmask_b32_e32 v45, v44, v45, vcc
	v_lshlrev_b32_e32 v113, 2, v45
	v_xor_b32_e32 v45, 2, v44
	s_ashr_i32 s4, s4, 8
	v_cmp_lt_i32_e32 vcc, v45, v46
	ds_write_b128 v20, v[2:5]
	ds_write_b128 v22, v[6:9]
	s_waitcnt vmcnt(7)
	ds_write_b128 v24, v[10:13]
	s_waitcnt vmcnt(6)
; #define LAS __attribute__((address_space(3)))
; __device__ __forceinline__ void sgu_phase(LAS unsigned char* lds, const bf16_t* PROJ, const float* VST, const bf16_t* SW, const float* ln_g, const float* ln_b, const float* sgu_b,
;                                           bf16_t* Y, float* SS, int bx, int G) {
;     ...
; #pragma unroll
;     for (int it = 0; it < 4; ++it) { const int p = tid + 512 * it, row = p >> 4, c16 = p & 15;
;         *(LAS u32x4*)(lds + SG_W + row * SG_ROWB + c16 * 16) = *(const u32x4*)(SW + (size_t)(h * 128 + row) * 128 + c16 * 8); }
;     const int dch = tid & 127; const float gch = ln_g[h * 128 + dch], bch = ln_b[h * 128 + dch];
;     const int dp = wid >> 1, th = wid & 1;
;     float bias[4];
; #pragma unroll
;     for (int jj = 0; jj < 4; ++jj) bias[jj] = sgu_b[h * 128 + 16 * (4 * th + jj) + fr];
;     u32x4 vst[4]; f32x4 sp[2];
;     ...
;     SGU_LOAD(cc);
	ds_write_b128 v18, v[14:17]
	v_add_u32_e32 v2, s16, v34
	v_ashrrev_i32_e32 v2, 4, v2
	v_add_u32_e32 v4, s16, v33
	v_ashrrev_i32_e32 v3, 31, v2
	v_ashrrev_i32_e32 v4, 4, v4
	v_lshlrev_b64 v[2:3], 13, v[2:3]
	v_ashrrev_i32_e32 v5, 31, v4
	v_lshl_add_u64 v[2:3], v[100:101], 0, v[2:3]
	v_lshlrev_b64 v[4:5], 13, v[4:5]
	v_lshl_add_u64 v[4:5], v[100:101], 0, v[4:5]
	global_load_dwordx4 v[14:17], v[2:3], off
	global_load_dwordx4 v[10:13], v[4:5], off
	v_add_u32_e32 v2, s16, v32
	v_ashrrev_i32_e32 v2, 4, v2
	v_ashrrev_i32_e32 v3, 31, v2
	v_lshlrev_b64 v[2:3], 13, v[2:3]
	v_lshl_add_u64 v[18:19], v[100:101], 0, v[2:3]
	v_add_u32_e32 v2, s16, v31
	v_ashrrev_i32_e32 v2, 4, v2
	v_ashrrev_i32_e32 v3, 31, v2
	v_lshlrev_b64 v[2:3], 13, v[2:3]
	v_lshl_add_u64 v[20:21], v[100:101], 0, v[2:3]
	global_load_dwordx4 v[6:9], v[18:19], off
	global_load_dwordx4 v[2:5], v[20:21], off
	v_add_u32_e32 v18, s16, v42
	v_ashrrev_i32_e32 v19, 31, v18
	v_lshlrev_b64 v[18:19], 7, v[18:19]
	v_lshl_add_u64 v[18:19], s[54:55], 0, v[18:19]
	v_lshl_add_u64 v[28:29], v[18:19], 0, v[98:99]
	global_load_dwordx4 v[18:21], v[28:29], off offset:16
	global_load_dwordx4 v[22:25], v[28:29], off
	s_ashr_i32 s5, s4, 31
	s_add_i32 s14, 0, 0x19c00
	v_cndmask_b32_e32 v45, v44, v45, vcc
	s_add_i32 s15, 0, 0x19800
	s_add_i32 s19, 0, 0x19a00
	s_lshl_b64 s[4:5], s[4:5], 23
	v_lshlrev_b32_e32 v114, 2, v45
	v_and_b32_e32 v45, -4, v26
	s_add_u32 s4, s36, s4
	v_add_u32_e32 v115, s15, v45
	v_add_u32_e32 v116, s19, v45
	s_addc_u32 s5, s37, s5
	s_lshl_b32 s11, s10, 4
	v_lshlrev_b32_e32 v45, 5, v26
	v_bfe_u32 v35, v26, 4, 2
	s_and_b32 s11, s11, 0xe00
	v_and_b32_e32 v45, 0x1e0, v45
	v_or_b32_e32 v45, s11, v45
	v_lshlrev_b32_e32 v117, 4, v35
	v_lshl_add_u64 v[102:103], s[54:55], 0, v[98:99]
	v_lshl_or_b32 v98, v45, 1, v117
	v_xor_b32_e32 v49, 16, v44
	v_lshl_add_u64 v[104:105], s[4:5], 0, v[98:99]
	s_add_i32 s4, s10, 0x1000
	v_cmp_lt_i32_e32 vcc, v49, v46
	s_ashr_i32 s4, s4, 8
	s_ashr_i32 s5, s4, 31
	v_cndmask_b32_e32 v49, v44, v49, vcc
	v_lshlrev_b32_e32 v119, 2, v49
	v_xor_b32_e32 v49, 32, v44
	s_lshl_b64 s[4:5], s[4:5], 23
	v_cmp_lt_i32_e32 vcc, v49, v46
	s_add_u32 s4, s36, s4
	v_ashrrev_i32_e32 v45, 7, v26
	v_cndmask_b32_e32 v44, v44, v49, vcc
	v_lshrrev_b32_e32 v29, 2, v26
	s_addc_u32 s5, s37, s5
	v_lshlrev_b32_e32 v120, 2, v44
	v_add_u32_e32 v44, 4, v45
	v_and_b32_e32 v38, -16, v31
	v_and_b32_e32 v39, -16, v32
	v_and_b32_e32 v40, -16, v33
	v_and_b32_e32 v41, -16, v34
	v_lshl_add_u64 v[106:107], s[4:5], 0, v[98:99]
	v_lshl_add_u32 v118, v36, 1, 0
	s_movk_i32 s4, 0x10e
	v_lshlrev_b32_e32 v47, 1, v26
	v_bfi_b32 v31, -16, v31, v29
	v_bfi_b32 v32, -16, v32, v29
	v_bfi_b32 v33, -16, v33, v29
	v_bfi_b32 v29, -16, v34, v29
	v_lshlrev_b32_e32 v34, 5, v45
	v_lshlrev_b32_e32 v49, 5, v44
	v_mad_u32_u24 v36, v36, s4, v118
	v_and_b32_e32 v47, 24, v47
	v_add_u32_e32 v48, s13, v117
	s_addk_i32 s10, 0x400
	s_lshl_b32 s4, s8, 10
	s_movk_i32 s13, 0x880
	v_add_u32_e32 v122, s15, v34
	v_add_u32_e32 v123, s19, v34
	v_or_b32_e32 v34, 16, v34
	v_add_u32_e32 v126, s15, v49
	v_add_u32_e32 v127, s19, v49
	v_or_b32_e32 v49, 16, v49
	v_cmp_eq_u32_e64 s[0:1], 0, v37
	v_or3_b32 v37, s9, v47, v37
	s_ashr_i32 s10, s10, 6
	s_and_b32 s55, s4, 0x400
	v_cmp_eq_u32_e64 s[8:9], 0, v35
	s_lshl_b32 s4, s7, 9
	v_mul_lo_u32 v121, v45, s13
	v_lshl_or_b32 v35, v45, 3, 1
	v_add_u32_e32 v124, s15, v34
	v_add_u32_e32 v125, s19, v34
	v_lshlrev_b32_e32 v34, 4, v45
	v_add_u32_e32 v128, s15, v49
	v_add_u32_e32 v129, s19, v49
	v_add_u32_e32 v49, 8, v45
	v_add_u32_e32 v45, 12, v45
	v_lshl_add_u32 v28, v26, 2, s14
	s_lshl_b32 s38, s17, 2
	s_ashr_i32 s11, s10, 31
	s_add_i32 s14, s14, s4
	v_lshlrev_b32_e32 v52, 5, v49
	v_lshlrev_b32_e32 v54, 5, v45
	v_lshl_or_b32 v50, v44, 3, 1
	v_add_u32_e32 v130, s15, v52
	v_add_u32_e32 v131, s19, v52
	v_lshl_or_b32 v53, v49, 3, 1
	v_or_b32_e32 v52, 16, v52
	v_add_u32_e32 v134, s15, v54
	v_add_u32_e32 v135, s19, v54
	v_lshl_or_b32 v55, v45, 3, 1
	v_or_b32_e32 v54, 16, v54
	s_bitcmp1_b32 s7, 0
	v_mul_lo_u32 v31, v31, s12
	v_mul_lo_u32 v32, v32, s12
	v_mul_lo_u32 v33, v33, s12
	v_mul_lo_u32 v29, v29, s12
	v_mul_lo_u32 v35, v35, s12
	v_mul_lo_u32 v50, v50, s12
	v_mul_lo_u32 v53, v53, s12
	v_add_u32_e32 v132, s15, v52
	v_mul_lo_u32 v55, v55, s12
	v_add_u32_e32 v136, s15, v54
	v_add_u32_e32 v137, s19, v54
	v_mul_lo_u32 v37, v37, s12
	v_or_b32_e32 v54, s18, v30
	s_cselect_b64 s[12:13], -1, 0
	s_or_b32 s15, s38, 1
	v_add_u32_e32 v133, s19, v52
	v_mul_u32_u24_e32 v56, 0x110, v54
	v_lshl_add_u32 v138, v54, 2, s14
	v_lshl_or_b32 v54, s15, 4, v30
	s_or_b32 s19, s38, 2
	s_or_b32 s38, s38, 3
	s_lshl_b32 s7, s17, 13
	v_mul_u32_u24_e32 v57, 0x110, v54
	s_lshl_b32 s15, s15, 11
	v_lshl_add_u32 v139, v54, 2, s14
	v_lshl_or_b32 v54, s19, 4, v30
	s_lshl_b32 s19, s19, 11
	s_lshl_b32 s59, s38, 11
	v_mul_u32_u24_e32 v58, 0x110, v54
	v_lshl_add_u32 v140, v54, 2, s14
	v_lshl_or_b32 v54, s38, 4, v30
	s_or_b32 s38, s7, s55
	s_or_b32 s39, s15, s55
	s_or_b32 s54, s19, s55
	s_or_b32 s55, s59, s55
	s_lshl_b32 s6, s6, 2
	v_lshl_add_u32 v141, v54, 2, s14
	s_add_u32 s14, s46, s6
	s_addc_u32 s15, s47, 0
	s_add_i32 s6, s20, s21
	s_lshl_b32 s6, s6, 7
	v_add_u32_e32 v47, 0, v117
	s_movk_i32 s4, 0x80
	v_lshlrev_b32_e32 v27, 9, v27
	v_add_u32_e32 v46, 0x2200, v121
	v_lshlrev_b32_e32 v44, 4, v44
	v_add_u32_e32 v51, 0x4400, v121
	v_lshlrev_b32_e32 v49, 4, v49
	v_add_u32_e32 v52, 0x6600, v121
	v_lshlrev_b32_e32 v45, 4, v45
	v_mul_u32_u24_e32 v59, 0x110, v54
	v_add_u32_e32 v142, s6, v42
	v_add_u32_e32 v143, s6, v41
	v_add_u32_e32 v144, s6, v40
	v_add_u32_e32 v145, s6, v39
	v_add_u32_e32 v146, s6, v38
	s_lshl_b32 s6, s20, 13
	s_lshl_b32 s7, s17, 12
	s_or_b32 s64, s16, s18
	s_mov_b32 s58, 0
	v_cmp_gt_i32_e64 s[4:5], s4, v26
	s_mul_i32 s59, s20, 48
	s_mul_i32 s60, s21, 48
	s_lshl_b32 s61, s21, 7
	v_add_u32_e32 v147, s16, v26
	v_lshlrev_b32_e32 v148, 6, v30
	s_or_b32 s62, s6, s7
	s_lshl_b32 s63, s21, 13
	v_or_b32_e32 v149, s64, v30
	v_add_u32_e32 v150, v43, v31
	v_add_u32_e32 v151, v43, v32
	v_add_u32_e32 v152, v43, v33
	v_add_u32_e32 v153, v43, v29
	s_mov_b32 s65, 0x3a800000
	s_mov_b32 s66, 0xf800000
	v_mov_b32_e32 v154, 0x260
	v_add_u32_e32 v155, v118, v35
	v_add_u32_e32 v156, v36, v34
	v_add_u32_e32 v157, v118, v46
	v_add_u32_e32 v158, v118, v50
	v_add_u32_e32 v159, v36, v44
	v_add_u32_e32 v160, v118, v51
	v_add_u32_e32 v161, v118, v53
	v_add_u32_e32 v162, v36, v49
	v_add_u32_e32 v163, v118, v52
	v_add_u32_e32 v164, v118, v55
	v_add_u32_e32 v165, v36, v45
	v_add_u32_e32 v166, v47, v37
	s_movk_i32 s67, 0x3c0
	v_add_u32_e32 v167, v28, v27
	v_add_u32_e32 v168, v48, v56
	v_add_u32_e32 v169, v48, v57
	v_add_u32_e32 v170, v48, v58
	v_add_u32_e32 v171, v48, v59
	s_waitcnt vmcnt(0)
	s_branch .Lsgu_body

; #define LAS __attribute__((address_space(3)))
; __device__ __forceinline__ void sgu_phase(LAS unsigned char* lds, const bf16_t* PROJ, const float* VST, const bf16_t* SW, const float* ln_g, const float* ln_b, const float* sgu_b,
;                                           bf16_t* Y, float* SS, int bx, int G) {
;     ...
;     for (; cc < 128; cc += step) {
;         const int T0 = cc * 128;
; #pragma unroll
;         for (int it = 0; it < 4; ++it) { const int p = tid + 512 * it, sb_ = p >> 6, row = 16 * (sb_ >> 2) + ((p >> 2) & 15), c16 = 4 * (sb_ & 3) + (p & 3); *(LAS u32x4*)(lds + SG_VS + row * SG_ROWB + c16 * 16) = vst[it]; }
;         { float s1 = (sp[0][0] + sp[0][2]) + (sp[1][0] + sp[1][2]), s2 = (sp[0][1] + sp[0][3]) + (sp[1][1] + sp[1][3]);
;           s1 += __shfl_xor(s1, 1); s1 += __shfl_xor(s1, 2); s2 += __shfl_xor(s2, 1); s2 += __shfl_xor(s2, 2);
;           const float mean = s1 * (1.0f / 1024.0f), var = fmaxf(s2 * (1.0f / 1024.0f) - mean * mean, 0.f);
;           if ((tid & 3) == 0) { meanp[tid >> 2] = mean; rstdp[tid >> 2] = 1.0f / sqrtf(var + EPS); } }
.LBB0_633:
	s_waitcnt vmcnt(4)
.Lsgu_body:
	v_add_f32_e32 v26, v22, v24
	v_add_f32_e32 v27, v18, v20
	v_add_f32_e32 v26, v26, v27
	v_add_f32_e32 v27, v23, v25
	v_add_f32_e32 v28, v19, v21
	v_add_f32_e32 v28, v27, v28
	ds_bpermute_b32 v29, v113, v26
	ds_bpermute_b32 v30, v113, v28
	ds_write_b128 v150, v[2:5]
	ds_write_b128 v151, v[6:9]
	ds_write_b128 v152, v[10:13]
	ds_write_b128 v153, v[14:17]
	s_waitcnt lgkmcnt(5)
	v_add_f32_e32 v26, v26, v29
	s_waitcnt lgkmcnt(4)
	v_add_f32_e32 v28, v28, v30
	ds_bpermute_b32 v27, v114, v26
	ds_bpermute_b32 v29, v114, v28
	s_and_saveexec_b64 s[16:17], s[0:1]
	s_cbranch_execz .LBB0_635
	s_waitcnt lgkmcnt(1)
	v_add_f32_e32 v26, v26, v27
	v_mul_f32_e32 v26, 0x3a800000, v26
	s_waitcnt lgkmcnt(0)
	v_add_f32_e32 v28, v28, v29
	v_mul_f32_e32 v27, v26, v26
	v_fma_f32 v27, v28, s65, -v27
	v_max_f32_e32 v27, 0, v27
	v_add_f32_e32 v27, 0x358637bd, v27
	v_mul_f32_e32 v28, 0x4f800000, v27
	v_cmp_gt_f32_e32 vcc, s66, v27
	ds_write_b32 v115, v26
	s_nop 0
	v_cndmask_b32_e32 v27, v27, v28, vcc
	v_sqrt_f32_e32 v28, v27
	s_nop 0
	v_add_u32_e32 v29, -1, v28
	v_fma_f32 v30, -v29, v28, v27
	v_cmp_ge_f32_e64 s[6:7], 0, v30
	v_add_u32_e32 v30, 1, v28
	s_nop 0
	v_cndmask_b32_e64 v29, v28, v29, s[6:7]
	v_fma_f32 v28, -v30, v28, v27
	v_cmp_lt_f32_e64 s[6:7], 0, v28
	s_nop 1
	v_cndmask_b32_e64 v28, v29, v30, s[6:7]
	v_mul_f32_e32 v29, 0x37800000, v28
	v_cndmask_b32_e32 v28, v28, v29, vcc
	v_cmp_class_f32_e32 vcc, v27, v154
	s_nop 1
	v_cndmask_b32_e32 v27, v28, v27, vcc
	v_div_scale_f32 v28, s[6:7], v27, v27, 1.0
	v_rcp_f32_e32 v29, v28
	s_nop 0
	v_fma_f32 v26, -v28, v29, 1.0
	v_fmac_f32_e32 v29, v26, v29
	v_div_scale_f32 v26, vcc, 1.0, v27, 1.0
	v_mul_f32_e32 v30, v26, v29
	v_fma_f32 v31, -v28, v30, v26
	v_fmac_f32_e32 v30, v31, v29
	v_fma_f32 v26, -v28, v30, v26
	v_div_fmas_f32 v26, v26, v29, v30
	v_div_fixup_f32 v26, v26, v27, 1.0
	ds_write_b32 v116, v26
